# P0 weight-conversion split rebalanced: the 64 conversion-only workgroups take 35 extra tiles each (was 13) so the 192 adaLN workgroups convert 13-14 tiles instead of 19
# speedup vs baseline: 1.0061x; 1.0061x over previous
.LBB0_140:
	s_sub_i32 s31, 0xe7f, s2
	s_ashr_i32 s6, s31, 31
	s_lshr_b32 s6, s6, 24
	s_add_i32 s6, s31, s6
	s_ashr_i32 s30, s6, 8
	s_load_dwordx4 s[8:11], s[0:1], 0xa8
	s_load_dwordx2 s[6:7], s[0:1], 0x68
	s_load_dwordx2 s[12:13], s[0:1], 0xc8
	s_load_dwordx2 s[14:15], s[0:1], 0xd8
	s_mov_b64 s[20:21], -1
	s_and_b64 vcc, exec, s[18:19]
	s_cbranch_vccz .LBB0_205
	s_add_i32 s18, s30, 35
	s_cmpk_lt_u32 s2, 0x1300
	s_cselect_b32 s34, s18, 35
	s_cmp_gt_i32 s34, 0
	s_cselect_b64 s[18:19], -1, 0
	s_cmp_lt_i32 s34, 1
	s_cbranch_scc1 .LBB0_144
	s_add_i32 s20, s2, 0xffffff40
	s_cmpk_lt_u32 s20, 0xe80
	s_cselect_b32 s21, 0, 0x200
	s_add_i32 s22, s21, s20
	s_cmpk_lt_u32 s22, 0x1640
	s_cselect_b32 s20, 2, 3
	s_cmpk_gt_u32 s22, 0x107f
	s_cselect_b32 s35, s20, 1
	s_cmpk_gt_u32 s22, 0xaff
	s_cselect_b64 s[20:21], -1, 0
	s_and_b64 s[20:21], s[20:21], exec
	s_cselect_b32 s23, s35, 0
	s_cmp_eq_u32 s23, 2
	s_cselect_b64 s[26:27], -1, 0
	s_movk_i32 s24, 0xef80
	s_and_b64 s[20:21], s[26:27], exec
	s_cselect_b32 s24, s24, 0xffffe9c0
	s_cselect_b32 s25, 46, 16
	s_cmpk_gt_u32 s22, 0xaff
	s_cselect_b64 s[20:21], -1, 0
	s_and_b64 s[20:21], s[20:21], exec
	s_cselect_b32 s25, s25, 0x58
	s_add_i32 s20, s22, 0xfffff500
	s_cmpk_lt_u32 s20, 0x580
	s_cselect_b64 s[28:29], -1, 0
	s_and_b64 s[20:21], s[28:29], exec
	s_cselect_b32 s24, 0xfffff500, s24
	s_cmpk_gt_u32 s22, 0xaff
	s_cselect_b64 s[20:21], -1, 0
	s_and_b64 vcc, s[20:21], exec
	s_cselect_b32 s20, s24, 0
	s_abs_i32 s21, s25
	s_waitcnt vmcnt(0)
	v_cvt_f32_u32_e32 v2, s21
	s_sub_i32 s36, 0, s21
	s_add_i32 s20, s20, s22
	s_ashr_i32 s20, s20, 2
	v_rcp_iflag_f32_e32 v2, v2
	s_abs_i32 s24, s20
	s_xor_b32 s22, s20, s25
	s_ashr_i32 s22, s22, 31
	v_mul_f32_e32 v2, 0x4f7ffffe, v2
	v_cvt_u32_f32_e32 v2, v2
	s_nop 0
	v_readfirstlane_b32 s37, v2
	s_mul_i32 s36, s36, s37
	s_mul_hi_u32 s36, s37, s36
	s_add_i32 s37, s37, s36
	s_mul_hi_u32 s36, s24, s37
	s_mul_i32 s37, s36, s21
	s_sub_i32 s24, s24, s37
	s_add_i32 s37, s36, 1
	s_sub_i32 s38, s24, s21
	s_cmp_ge_u32 s24, s21
	s_cselect_b32 s36, s37, s36
	s_cselect_b32 s24, s38, s24
	s_add_i32 s37, s36, 1
	s_cmp_ge_u32 s24, s21
	s_cselect_b32 s21, s37, s36
	s_xor_b32 s21, s21, s22
	s_sub_i32 s36, s21, s22
	s_mul_i32 s21, s36, s25
	s_sub_i32 s37, s20, s21
	s_cbranch_vccnz .LBB0_146
	s_lshl_b32 s21, s37, 6
	s_and_b32 s21, s21, 0xffffff80
	s_and_b32 s20, s37, 1
	s_add_i32 s22, s21, 0x1600
	s_cmp_eq_u32 s20, 0
	s_cselect_b32 s22, s21, s22
	s_mov_b64 s[24:25], 0
	s_waitcnt lgkmcnt(0)
	s_mov_b64 s[20:21], s[10:11]
	s_branch .LBB0_147

.LBB0_174:
	s_addk_i32 s42, 0xff80
	s_addk_i32 s43, 0xe6c0
	s_cmp_lt_u32 s45, 35
	s_cselect_b32 s28, s42, s43
	s_cmpk_lt_i32 s28, 0xe80
	s_cselect_b32 s20, 0, 0x200
	s_add_i32 s29, s20, s28
	s_cmpk_gt_i32 s29, 0xaff
	s_cselect_b64 s[20:21], -1, 0
	s_add_i32 s22, s29, 0xfffff500
	s_cmpk_lt_u32 s22, 0x580
	s_cselect_b64 s[22:23], -1, 0
	s_add_i32 s24, s29, 0xffffef80
	s_cmpk_lt_u32 s24, 0x5c0
	s_cselect_b64 s[24:25], -1, 0
	s_and_b64 s[26:27], s[24:25], exec
	s_cselect_b32 s42, s36, 0xffffe9c0
	s_and_b64 s[26:27], s[22:23], exec
	s_cselect_b32 s42, 0xfffff500, s42
	s_and_b64 s[26:27], s[20:21], exec
	s_cselect_b32 s26, s42, 0
	s_add_i32 s29, s26, s29
	s_and_b64 s[26:27], s[24:25], exec
	s_cselect_b32 s42, 46, 16
	s_and_b64 s[26:27], s[20:21], exec
	s_cselect_b32 s26, s42, 0x58
	s_abs_i32 s27, s26
	v_cvt_f32_u32_e32 v37, s27
	s_sub_i32 s44, 0, s27
	s_ashr_i32 s29, s29, 2
	s_abs_i32 s43, s29
	v_rcp_iflag_f32_e32 v37, v37
	s_ashr_i32 s42, s29, 31
	s_waitcnt lgkmcnt(0)
	s_barrier
	v_mul_f32_e32 v37, 0x4f7ffffe, v37
	v_cvt_u32_f32_e32 v37, v37
	ds_read2_b32 v[46:47], v154 offset1:132
	ds_read2_b32 v[48:49], v38 offset0:8 offset1:140
	ds_read2_b32 v[50:51], v39 offset0:16 offset1:148
	ds_read2_b32 v[52:53], v40 offset0:24 offset1:156
	ds_read2_b32 v[54:55], v41 offset0:32 offset1:164
	ds_read2_b32 v[56:57], v42 offset0:40 offset1:172
	ds_read2_b32 v[58:59], v43 offset0:48 offset1:180
	ds_read2_b32 v[60:61], v44 offset0:56 offset1:188
	s_waitcnt lgkmcnt(7)
	v_cvt_pk_bf16_f32 v38, v46, v47
	v_readfirstlane_b32 s45, v37
	s_mul_i32 s44, s44, s45
	s_mul_hi_u32 s44, s45, s44
	s_add_i32 s45, s45, s44
	s_mul_hi_u32 s44, s43, s45
	s_mul_i32 s45, s44, s27
	s_sub_i32 s43, s43, s45
	s_add_i32 s45, s44, 1
	s_sub_i32 s46, s43, s27
	s_cmp_ge_u32 s43, s27
	s_cselect_b32 s44, s45, s44
	s_cselect_b32 s43, s46, s43
	s_add_i32 s45, s44, 1
	s_cmp_ge_u32 s43, s27
	s_cselect_b32 s27, s45, s44
	s_xor_b32 s27, s27, s42
	s_sub_i32 s27, s27, s42
	s_mul_i32 s26, s27, s26
	s_sub_i32 s26, s29, s26
	s_and_b64 s[24:25], s[24:25], exec
	s_cselect_b32 s29, s39, 0x5900000
	s_and_b64 s[24:25], s[22:23], exec
	s_cselect_b32 s24, 0x2c00000, s29
	s_and_b64 s[20:21], s[20:21], exec
	s_cselect_b32 s21, s24, 0
	s_lshl_b32 s24, s28, 6
	s_lshl_b32 s20, s27, 8
	s_and_b32 s24, s24, 0xc0
	s_or_b32 s20, s20, s24
	s_and_b64 s[22:23], s[22:23], exec
	s_cselect_b32 s24, 0x1600, s37
	s_add_u32 s22, s14, s21
	v_lshl_add_u32 v37, s26, 7, v153
	s_addc_u32 s23, s15, 0
	v_mad_i64_i32 v[46:47], s[24:25], s24, v37, 0
	v_lshl_add_u64 v[46:47], v[46:47], 1, s[22:23]
	s_ashr_i32 s21, s20, 31
	v_lshl_add_u64 v[46:47], s[20:21], 1, v[46:47]
	s_waitcnt lgkmcnt(6)
	v_cvt_pk_bf16_f32 v39, v48, v49
	s_waitcnt lgkmcnt(5)
	v_cvt_pk_bf16_f32 v40, v50, v51
	s_waitcnt lgkmcnt(4)
	v_cvt_pk_bf16_f32 v41, v52, v53
	v_lshl_add_u64 v[46:47], v[46:47], 0, v[34:35]
	s_waitcnt lgkmcnt(3)
	v_cvt_pk_bf16_f32 v42, v54, v55
	s_waitcnt lgkmcnt(2)
	v_cvt_pk_bf16_f32 v43, v56, v57
	s_waitcnt lgkmcnt(1)
	v_cvt_pk_bf16_f32 v44, v58, v59
	s_waitcnt lgkmcnt(0)
	v_cvt_pk_bf16_f32 v45, v60, v61
	global_store_dwordx4 v[46:47], v[38:41], off
	global_store_dwordx4 v[46:47], v[42:45], off offset:16
	s_barrier

.LBB0_176:
	s_add_i32 s42, s2, s40
	s_add_i32 s43, s2, s35
	s_add_i32 s41, s44, 2
	s_cmp_ge_i32 s41, s34
	s_cselect_b64 s[18:19], -1, 0
	s_and_b64 vcc, exec, s[18:19]
	s_waitcnt vmcnt(0)
	ds_write_b128 v149, v[6:9]
	ds_write_b128 v150, v[2:5] offset:8448
	ds_write_b128 v151, v[14:17] offset:16896
	ds_write_b128 v152, v[10:13] offset:25344
	s_cbranch_vccnz .LBB0_190
	s_sub_i32 s20, s42, 64
	s_add_i32 s21, s43, 0xffffe7c0
	s_cmp_lt_u32 s44, 33
	s_cselect_b32 s23, s20, s21
	s_cmpk_lt_i32 s23, 0xe80
	s_cselect_b32 s20, 0, 0x200
	s_add_i32 s22, s20, s23
	s_cmpk_lt_u32 s22, 0x1640
	s_cselect_b32 s20, 2, 3
	s_cmpk_gt_u32 s22, 0x107f
	s_cselect_b32 s46, s20, 1
	s_cmpk_gt_i32 s22, 0xaff
	s_cselect_b64 s[20:21], -1, 0
	s_and_b64 s[20:21], s[20:21], exec
	s_cselect_b32 s45, s46, 0
	s_cmp_eq_u32 s45, 2
	s_cselect_b64 s[26:27], -1, 0
	s_and_b64 s[20:21], s[26:27], exec
	s_cselect_b32 s24, s36, 0xffffe9c0
	s_cselect_b32 s25, 46, 16
	s_cmpk_gt_i32 s22, 0xaff
	s_cselect_b64 s[20:21], -1, 0
	s_and_b64 s[20:21], s[20:21], exec
	s_cselect_b32 s25, s25, 0x58
	s_add_i32 s20, s22, 0xfffff500
	s_cmpk_lt_u32 s20, 0x580
	s_cselect_b64 s[28:29], -1, 0
	s_and_b64 s[20:21], s[28:29], exec
	s_cselect_b32 s24, 0xfffff500, s24
	s_cmpk_gt_i32 s22, 0xaff
	s_cselect_b64 s[20:21], -1, 0
	s_and_b64 vcc, s[20:21], exec
	s_cselect_b32 s20, s24, 0
	s_abs_i32 s21, s25
	v_cvt_f32_u32_e32 v2, s21
	s_sub_i32 s47, 0, s21
	s_add_i32 s20, s20, s22
	s_ashr_i32 s20, s20, 2
	v_rcp_iflag_f32_e32 v2, v2
	s_abs_i32 s24, s20
	s_xor_b32 s22, s20, s25
	s_ashr_i32 s22, s22, 31
	v_mul_f32_e32 v2, 0x4f7ffffe, v2
	v_cvt_u32_f32_e32 v2, v2
	s_nop 0
	v_readfirstlane_b32 s48, v2
	s_mul_i32 s47, s47, s48
	s_mul_hi_u32 s47, s48, s47
	s_add_i32 s48, s48, s47
	s_mul_hi_u32 s47, s24, s48
	s_mul_i32 s48, s47, s21
	s_sub_i32 s24, s24, s48
	s_add_i32 s48, s47, 1
	s_sub_i32 s49, s24, s21
	s_cmp_ge_u32 s24, s21
	s_cselect_b32 s47, s48, s47
	s_cselect_b32 s24, s49, s24
	s_add_i32 s48, s47, 1
	s_cmp_ge_u32 s24, s21
	s_cselect_b32 s21, s48, s47
	s_xor_b32 s21, s21, s22
	s_sub_i32 s47, s21, s22
	s_mul_i32 s21, s47, s25
	s_sub_i32 s48, s20, s21
	s_mov_b64 s[24:25], -1
	s_cbranch_vccnz .LBB0_179
	s_lshl_b32 s21, s48, 6
	s_and_b32 s21, s21, 0xffffff80
	s_and_b32 s20, s48, 1
	s_add_i32 s22, s21, 0x1600
	s_cmp_eq_u32 s20, 0
	s_cselect_b32 s22, s21, s22
	s_mov_b64 s[24:25], 0
	s_waitcnt lgkmcnt(0)
	s_mov_b64 s[20:21], s[10:11]

.LBB0_190:
	s_add_i32 s20, s42, 0xffffff40
	s_add_i32 s21, s43, 0xffffe5c0
	s_cmp_lt_u32 s44, 35
	s_cselect_b32 s28, s20, s21
	s_cmpk_lt_i32 s28, 0xe80
	s_cselect_b32 s20, 0, 0x200
	s_add_i32 s29, s20, s28
	s_cmpk_gt_i32 s29, 0xaff
	s_cselect_b64 s[20:21], -1, 0
	s_add_i32 s22, s29, 0xfffff500
	s_cmpk_lt_u32 s22, 0x580
	s_cselect_b64 s[22:23], -1, 0
	s_add_i32 s24, s29, 0xffffef80
	s_cmpk_lt_u32 s24, 0x5c0
	s_cselect_b64 s[24:25], -1, 0
	s_and_b64 s[26:27], s[24:25], exec
	s_cselect_b32 s45, s36, 0xffffe9c0
	s_and_b64 s[26:27], s[22:23], exec
	s_cselect_b32 s45, 0xfffff500, s45
	s_and_b64 s[26:27], s[20:21], exec
	s_cselect_b32 s26, s45, 0
	s_add_i32 s29, s26, s29
	s_and_b64 s[26:27], s[24:25], exec
	s_cselect_b32 s45, 46, 16
	s_and_b64 s[26:27], s[20:21], exec
	s_cselect_b32 s26, s45, 0x58
	s_abs_i32 s27, s26
	v_cvt_f32_u32_e32 v37, s27
	s_sub_i32 s47, 0, s27
	s_ashr_i32 s29, s29, 2
	s_abs_i32 s46, s29
	v_rcp_iflag_f32_e32 v37, v37
	s_ashr_i32 s45, s29, 31
	v_add_u32_e32 v38, 0x400, v154
	v_add_u32_e32 v39, 0x800, v154
	v_mul_f32_e32 v37, 0x4f7ffffe, v37
	v_cvt_u32_f32_e32 v37, v37
	v_add_u32_e32 v41, 0x1000, v154
	s_waitcnt lgkmcnt(0)
	s_barrier
	v_readfirstlane_b32 s48, v37
	s_mul_i32 s47, s47, s48
	s_mul_hi_u32 s47, s48, s47
	s_add_i32 s48, s48, s47
	s_mul_hi_u32 s47, s46, s48
	s_mul_i32 s48, s47, s27
	s_sub_i32 s46, s46, s48
	s_add_i32 s48, s47, 1
	s_sub_i32 s49, s46, s27
	s_cmp_ge_u32 s46, s27
	s_cselect_b32 s47, s48, s47
	s_cselect_b32 s46, s49, s46
	s_add_i32 s48, s47, 1
	s_cmp_ge_u32 s46, s27
	s_cselect_b32 s27, s48, s47
	s_xor_b32 s27, s27, s45
	s_sub_i32 s27, s27, s45
	s_mul_i32 s26, s27, s26
	s_sub_i32 s26, s29, s26
	s_and_b64 s[24:25], s[24:25], exec
	s_cselect_b32 s29, s39, 0x5900000
	s_and_b64 s[24:25], s[22:23], exec
	s_cselect_b32 s24, 0x2c00000, s29
	s_and_b64 s[20:21], s[20:21], exec
	s_cselect_b32 s21, s24, 0
	s_lshl_b32 s24, s28, 6
	ds_read2_b32 v[46:47], v154 offset1:132
	ds_read2_b32 v[48:49], v38 offset0:8 offset1:140
	ds_read2_b32 v[50:51], v39 offset0:16 offset1:148
	ds_read2_b32 v[54:55], v41 offset0:32 offset1:164
	s_lshl_b32 s20, s27, 8
	s_and_b32 s24, s24, 0xc0
	s_or_b32 s20, s20, s24
	v_add_u32_e32 v40, 0xc00, v154
	s_and_b64 s[22:23], s[22:23], exec
	ds_read2_b32 v[52:53], v40 offset0:24 offset1:156
	v_add_u32_e32 v42, 0x1400, v154
	v_add_u32_e32 v43, 0x1800, v154
	v_add_u32_e32 v44, 0x1c00, v154
	s_cselect_b32 s24, 0x1600, s37
	s_add_u32 s22, s14, s21
	ds_read2_b32 v[56:57], v42 offset0:40 offset1:172
	ds_read2_b32 v[58:59], v43 offset0:48 offset1:180
	ds_read2_b32 v[60:61], v44 offset0:56 offset1:188
	v_lshl_add_u32 v37, s26, 7, v153
	s_addc_u32 s23, s15, 0
	s_waitcnt lgkmcnt(7)
	v_cvt_pk_bf16_f32 v46, v46, v47
	s_waitcnt lgkmcnt(6)
	v_cvt_pk_bf16_f32 v47, v48, v49
	s_waitcnt lgkmcnt(5)
	v_cvt_pk_bf16_f32 v48, v50, v51
	s_waitcnt lgkmcnt(4)
	v_cvt_pk_bf16_f32 v50, v54, v55
	v_mad_i64_i32 v[54:55], s[24:25], s24, v37, 0
	v_lshl_add_u64 v[54:55], v[54:55], 1, s[22:23]
	s_ashr_i32 s21, s20, 31
	v_lshl_add_u64 v[54:55], s[20:21], 1, v[54:55]
	s_add_i32 s45, s44, 1
	s_waitcnt lgkmcnt(3)
	v_cvt_pk_bf16_f32 v49, v52, v53
	v_lshl_add_u64 v[54:55], v[54:55], 0, v[34:35]
	s_cmp_ge_i32 s45, s34
	s_waitcnt lgkmcnt(2)
	v_cvt_pk_bf16_f32 v51, v56, v57
	s_waitcnt lgkmcnt(1)
	v_cvt_pk_bf16_f32 v52, v58, v59
	s_waitcnt lgkmcnt(0)
	v_cvt_pk_bf16_f32 v53, v60, v61
	global_store_dwordx4 v[54:55], v[46:49], off
	global_store_dwordx4 v[54:55], v[50:53], off offset:16
	s_barrier
	s_cbranch_scc1 .LBB0_175
	s_add_i32 s20, s44, 3
	s_cmp_ge_i32 s20, s34
	ds_write_b128 v149, v[18:21]
	ds_write_b128 v150, v[22:25] offset:8448
	ds_write_b128 v151, v[26:29] offset:16896
	ds_write_b128 v152, v[30:33] offset:25344
	s_cbranch_scc1 .LBB0_174
	s_add_i32 s20, s43, 0xffffe8c0
	s_cmp_lt_u32 s44, 32
	s_cselect_b32 s23, s42, s20
	s_cmpk_lt_i32 s23, 0xe80
	s_cselect_b32 s20, 0, 0x200
	s_add_i32 s22, s20, s23
	s_cmpk_lt_u32 s22, 0x1640
	s_cselect_b32 s20, 2, 3
	s_cmpk_gt_u32 s22, 0x107f
	s_cselect_b32 s46, s20, 1
	s_cmpk_gt_i32 s22, 0xaff
	s_cselect_b64 s[20:21], -1, 0
	s_and_b64 s[20:21], s[20:21], exec
	s_cselect_b32 s44, s46, 0
	s_cmp_eq_u32 s44, 2
	s_cselect_b64 s[26:27], -1, 0
	s_and_b64 s[20:21], s[26:27], exec
	s_cselect_b32 s24, s36, 0xffffe9c0
	s_cselect_b32 s25, 46, 16
	s_cmpk_gt_i32 s22, 0xaff
	s_cselect_b64 s[20:21], -1, 0
	s_and_b64 s[20:21], s[20:21], exec
	s_cselect_b32 s25, s25, 0x58
	s_add_i32 s20, s22, 0xfffff500
	s_cmpk_lt_u32 s20, 0x580
	s_cselect_b64 s[28:29], -1, 0
	s_and_b64 s[20:21], s[28:29], exec
	s_cselect_b32 s24, 0xfffff500, s24
	s_cmpk_gt_i32 s22, 0xaff
	s_cselect_b64 s[20:21], -1, 0
	s_and_b64 vcc, s[20:21], exec
	s_cselect_b32 s20, s24, 0
	s_abs_i32 s21, s25
	v_cvt_f32_u32_e32 v18, s21
	s_sub_i32 s47, 0, s21
	s_add_i32 s20, s20, s22
	s_ashr_i32 s20, s20, 2
	v_rcp_iflag_f32_e32 v18, v18
	s_abs_i32 s24, s20
	s_xor_b32 s22, s20, s25
	s_ashr_i32 s22, s22, 31
	v_mul_f32_e32 v18, 0x4f7ffffe, v18
	v_cvt_u32_f32_e32 v18, v18
	s_nop 0
	v_readfirstlane_b32 s48, v18
	s_mul_i32 s47, s47, s48
	s_mul_hi_u32 s47, s48, s47
	s_add_i32 s48, s48, s47
	s_mul_hi_u32 s47, s24, s48
	s_mul_i32 s48, s47, s21
	s_sub_i32 s24, s24, s48
	s_add_i32 s48, s47, 1
	s_sub_i32 s49, s24, s21
	s_cmp_ge_u32 s24, s21
	s_cselect_b32 s47, s48, s47
	s_cselect_b32 s24, s49, s24
	s_add_i32 s48, s47, 1
	s_cmp_ge_u32 s24, s21
	s_cselect_b32 s21, s48, s47
	s_xor_b32 s21, s21, s22
	s_sub_i32 s47, s21, s22
	s_mul_i32 s21, s47, s25
	s_sub_i32 s48, s20, s21
	s_mov_b64 s[24:25], -1
	s_cbranch_vccnz .LBB0_194
	s_lshl_b32 s21, s48, 6
	s_and_b32 s21, s21, 0xffffff80
	s_and_b32 s20, s48, 1
	s_add_i32 s22, s21, 0x1600
	s_cmp_eq_u32 s20, 0
	s_cselect_b32 s22, s21, s22
	s_mov_b64 s[24:25], 0
	s_mov_b64 s[20:21], s[10:11]

.LBB0_205:
	s_and_b64 vcc, exec, s[20:21]
	s_cbranch_vccz .LBB0_243
	s_waitcnt vmcnt(0)
	v_mov_b32_e32 v2, 0
	s_cmpk_gt_i32 s31, 0xff
	s_cselect_b64 s[18:19], -1, 0
	s_cmpk_lt_i32 s31, 0x100
	v_mov_b32_e32 v3, v2
	v_mov_b32_e32 v4, v2
	v_mov_b32_e32 v5, v2
	v_mov_b32_e32 v6, v2
	v_mov_b32_e32 v7, v2
	v_mov_b32_e32 v8, v2
	v_mov_b32_e32 v9, v2
	v_mov_b32_e32 v10, v2
	v_mov_b32_e32 v11, v2
	v_mov_b32_e32 v12, v2
	v_mov_b32_e32 v13, v2
	v_mov_b32_e32 v14, v2
	v_mov_b32_e32 v15, v2
	v_mov_b32_e32 v16, v2
	v_mov_b32_e32 v17, v2
	s_cbranch_scc1 .LBB0_208
	s_add_i32 s20, s2, 0x8c0
	s_ashr_i32 s20, s20, 2
	s_mul_hi_i32 s21, s20, 0x2e8ba2e9
	s_lshr_b32 s22, s21, 31
	s_ashr_i32 s21, s21, 4
	s_add_i32 s21, s21, s22
	s_mul_i32 s22, s21, 0x58
	s_sub_i32 s20, s20, s22
	s_and_b32 s22, s20, 1
	s_lshl_b32 s20, s20, 6
	s_and_b32 s20, s20, 0xffffff80
	s_add_i32 s23, s20, 0x1600
	s_cmp_eq_u32 s22, 0
	s_cselect_b32 s20, s20, s23
	s_lshl_b32 s21, s21, 8
	s_or_b32 s22, s21, s3
	v_or_b32_e32 v2, s22, v146
	s_ashr_i32 s21, s20, 31
	s_mov_b32 s24, 0xb000
	s_waitcnt lgkmcnt(0)
	v_mov_b64_e32 v[10:11], s[10:11]
	v_or_b32_e32 v4, s22, v147
	v_or_b32_e32 v18, 32, v2
	v_add_u32_e32 v20, s22, v148
	v_mad_i64_i32 v[2:3], s[22:23], v2, s24, v[10:11]
	s_lshl_b64 s[20:21], s[20:21], 2
	v_lshl_add_u64 v[2:3], v[2:3], 0, s[20:21]
	v_lshlrev_b32_e32 v12, 2, v156
	v_mov_b32_e32 v13, 0
	v_lshl_add_u64 v[14:15], v[2:3], 0, v[12:13]
	v_mad_i64_i32 v[2:3], s[22:23], v4, s24, v[10:11]
	v_lshl_add_u64 v[2:3], v[2:3], 0, s[20:21]
	v_lshl_add_u64 v[16:17], v[2:3], 0, v[12:13]
	global_load_dwordx4 v[2:5], v[14:15], off
	global_load_dwordx4 v[6:9], v[16:17], off
	v_mad_i64_i32 v[14:15], s[22:23], v18, s24, v[10:11]
	v_lshl_add_u64 v[14:15], v[14:15], 0, s[20:21]
	v_mad_i64_i32 v[10:11], s[22:23], v20, s24, v[10:11]
	v_lshl_add_u64 v[18:19], v[14:15], 0, v[12:13]
	v_lshl_add_u64 v[10:11], v[10:11], 0, s[20:21]
	v_lshl_add_u64 v[20:21], v[10:11], 0, v[12:13]
	global_load_dwordx4 v[10:13], v[18:19], off
	global_load_dwordx4 v[14:17], v[20:21], off
.LBB0_208:
	s_cmpk_lt_i32 s31, 0x200
	s_cbranch_scc1 .LBB0_210
	s_add_i32 s20, s2, 0x9c0
	s_ashr_i32 s20, s20, 2
	s_mul_hi_i32 s21, s20, 0x2e8ba2e9
	s_lshr_b32 s22, s21, 31
	s_ashr_i32 s21, s21, 4
	s_add_i32 s21, s21, s22
	s_mul_i32 s22, s21, 0x58
	s_sub_i32 s20, s20, s22
	s_and_b32 s22, s20, 1
	s_lshl_b32 s20, s20, 6
	s_and_b32 s20, s20, 0xffffff80
	s_add_i32 s23, s20, 0x1600
	s_cmp_eq_u32 s22, 0
	s_cselect_b32 s20, s20, s23
	s_lshl_b32 s21, s21, 8
	s_or_b32 s22, s21, s3
	v_or_b32_e32 v18, s22, v146
	s_ashr_i32 s21, s20, 31
	s_mov_b32 s24, 0xb000
	s_waitcnt lgkmcnt(0)
	v_mov_b64_e32 v[26:27], s[10:11]
	v_or_b32_e32 v20, s22, v147
	v_or_b32_e32 v34, 32, v18
	v_add_u32_e32 v36, s22, v148
	v_mad_i64_i32 v[18:19], s[22:23], v18, s24, v[26:27]
	s_lshl_b64 s[20:21], s[20:21], 2
	v_lshl_add_u64 v[18:19], v[18:19], 0, s[20:21]
	v_lshlrev_b32_e32 v28, 2, v156
	v_mov_b32_e32 v29, 0
	v_lshl_add_u64 v[30:31], v[18:19], 0, v[28:29]
	v_mad_i64_i32 v[18:19], s[22:23], v20, s24, v[26:27]
	v_lshl_add_u64 v[18:19], v[18:19], 0, s[20:21]
	v_lshl_add_u64 v[32:33], v[18:19], 0, v[28:29]
	global_load_dwordx4 v[18:21], v[30:31], off
	global_load_dwordx4 v[22:25], v[32:33], off
	v_mad_i64_i32 v[30:31], s[22:23], v34, s24, v[26:27]
	v_lshl_add_u64 v[30:31], v[30:31], 0, s[20:21]
	v_mad_i64_i32 v[26:27], s[22:23], v36, s24, v[26:27]
	v_lshl_add_u64 v[34:35], v[30:31], 0, v[28:29]
	v_lshl_add_u64 v[26:27], v[26:27], 0, s[20:21]
	v_lshl_add_u64 v[36:37], v[26:27], 0, v[28:29]
	global_load_dwordx4 v[26:29], v[34:35], off
	global_load_dwordx4 v[30:33], v[36:37], off
	s_andn2_b64 vcc, exec, s[18:19]
	s_cbranch_vccz .LBB0_211
	s_branch .LBB0_243

.LBB0_211:
	s_add_i32 s28, s2, 0xbc0
	s_mov_b32 s29, 3
	s_movk_i32 s31, 0xef80
	s_movk_i32 s34, 0x800
	s_movk_i32 s35, 0x1610
	v_mov_b32_e32 v35, 0
	s_mov_b32 s36, 0x4200000
	v_lshlrev_b32_e32 v34, 1, v157
	v_lshlrev_b32_e32 v36, 2, v156
	s_branch .LBB0_215
